# plus DA item epilogue: 15 subln loads issued together with counted waits
# speedup vs baseline: 1.0120x; 1.0010x over previous
.LBB0_302:
	s_andn2_b64 vcc, exec, s[2:3]
	s_waitcnt lgkmcnt(0)
	s_barrier
	s_cbranch_vccnz .LBB0_279
	v_readlane_b32 s64, v239, 0
	ds_read2st64_b32 v[96:97], v2 offset1:1
	ds_read2st64_b32 v[4:5], v2 offset0:2 offset1:3
	ds_read2st64_b32 v[98:99], v2 offset0:4 offset1:5
	ds_read2st64_b32 v[100:101], v2 offset0:6 offset1:7
	ds_read2st64_b32 v[102:103], v2 offset0:8 offset1:9
	ds_read2st64_b32 v[104:105], v2 offset0:10 offset1:11
	ds_read2st64_b32 v[106:107], v2 offset0:12 offset1:13
	ds_read2st64_b32 v[108:109], v2 offset0:14 offset1:15
	ds_read2st64_b32 v[110:111], v2 offset0:16 offset1:17
	ds_read2st64_b32 v[112:113], v2 offset0:18 offset1:19
	ds_read2st64_b32 v[114:115], v2 offset0:20 offset1:21
	ds_read2st64_b32 v[116:117], v2 offset0:22 offset1:23
	ds_read2st64_b32 v[118:119], v2 offset0:24 offset1:25
	ds_read2st64_b32 v[120:121], v2 offset0:26 offset1:27
	ds_read2st64_b32 v[122:123], v2 offset0:28 offset1:29
	ds_read2st64_b32 v[124:125], v2 offset0:30 offset1:31
	ds_read2st64_b32 v[126:127], v2 offset0:32 offset1:33
	ds_read2st64_b32 v[128:129], v2 offset0:34 offset1:35
	ds_read2st64_b32 v[130:131], v2 offset0:36 offset1:37
	ds_read2st64_b32 v[132:133], v2 offset0:38 offset1:39
	ds_read2st64_b32 v[94:95], v2 offset0:40 offset1:41
	ds_read2st64_b32 v[134:135], v2 offset0:42 offset1:43
	ds_read2st64_b32 v[90:91], v2 offset0:44 offset1:45
	ds_read2st64_b32 v[92:93], v2 offset0:46 offset1:47
	ds_read2st64_b32 v[86:87], v2 offset0:48 offset1:49
	ds_read2st64_b32 v[88:89], v2 offset0:50 offset1:51
	ds_read2st64_b32 v[82:83], v2 offset0:52 offset1:53
	ds_read2st64_b32 v[84:85], v2 offset0:54 offset1:55
	ds_read2st64_b32 v[14:15], v2 offset0:56 offset1:57
	ds_read2st64_b32 v[80:81], v2 offset0:58 offset1:59
	ds_read2st64_b32 v[10:11], v2 offset0:60 offset1:61
	ds_read2st64_b32 v[12:13], v2 offset0:62 offset1:63
	v_readlane_b32 s74, v239, 10
	v_readlane_b32 s75, v239, 11
	s_waitcnt lgkmcnt(14)
	v_pk_fma_f32 v[8:9], v[66:67], v[0:1], v[4:5] op_sel_hi:[1,0,1] neg_lo:[0,0,1] neg_hi:[0,0,1]
	v_pk_fma_f32 v[66:67], v[64:65], v[0:1], v[96:97] op_sel_hi:[1,0,1] neg_lo:[0,0,1] neg_hi:[0,0,1]
	v_mul_f32_e32 v96, v9, v9
	v_mul_f32_e32 v64, v67, v67
	v_pk_fma_f32 v[64:65], v[66:67], v[66:67], v[64:65] op_sel_hi:[1,1,0]
	global_load_dwordx4 v[2:5], v146, s[74:75]
	v_pk_fma_f32 v[64:65], v[8:9], v[8:9], v[64:65]
	v_pk_fma_f32 v[76:77], v[76:77], v[0:1], v[106:107] op_sel_hi:[1,0,1] neg_lo:[0,0,1] neg_hi:[0,0,1]
	v_pk_add_f32 v[96:97], v[64:65], v[96:97] op_sel_hi:[1,0]
	v_pk_fma_f32 v[64:65], v[70:71], v[0:1], v[100:101] op_sel_hi:[1,0,1] neg_lo:[0,0,1] neg_hi:[0,0,1]
	v_pk_fma_f32 v[70:71], v[68:69], v[0:1], v[98:99] op_sel_hi:[1,0,1] neg_lo:[0,0,1] neg_hi:[0,0,1]
	v_pk_fma_f32 v[50:51], v[50:51], v[0:1], v[112:113] op_sel_hi:[1,0,1] neg_lo:[0,0,1] neg_hi:[0,0,1]
	v_pk_fma_f32 v[68:69], v[70:71], v[70:71], v[96:97]
	v_mul_f32_e32 v96, v71, v71
	v_pk_add_f32 v[68:69], v[68:69], v[96:97] op_sel_hi:[1,0]
	v_mul_f32_e32 v96, v65, v65
	v_pk_fma_f32 v[68:69], v[64:65], v[64:65], v[68:69]
	v_pk_fma_f32 v[60:61], v[60:61], v[0:1], v[122:123] op_sel_hi:[1,0,1] neg_lo:[0,0,1] neg_hi:[0,0,1]
	v_pk_add_f32 v[96:97], v[68:69], v[96:97] op_sel_hi:[1,0]
	v_pk_fma_f32 v[68:69], v[74:75], v[0:1], v[104:105] op_sel_hi:[1,0,1] neg_lo:[0,0,1] neg_hi:[0,0,1]
	v_pk_fma_f32 v[74:75], v[72:73], v[0:1], v[102:103] op_sel_hi:[1,0,1] neg_lo:[0,0,1] neg_hi:[0,0,1]
	v_pk_fma_f32 v[34:35], v[34:35], v[0:1], v[128:129] op_sel_hi:[1,0,1] neg_lo:[0,0,1] neg_hi:[0,0,1]
	v_pk_fma_f32 v[72:73], v[74:75], v[74:75], v[96:97]
	v_mul_f32_e32 v96, v75, v75
	v_pk_add_f32 v[72:73], v[72:73], v[96:97] op_sel_hi:[1,0]
	v_mul_f32_e32 v96, v69, v69
	v_pk_fma_f32 v[72:73], v[68:69], v[68:69], v[72:73]
	s_waitcnt lgkmcnt(11)
	v_pk_fma_f32 v[40:41], v[40:41], v[0:1], v[94:95] op_sel_hi:[1,0,1] neg_lo:[0,0,1] neg_hi:[0,0,1]
	v_pk_add_f32 v[96:97], v[72:73], v[96:97] op_sel_hi:[1,0]
	v_pk_fma_f32 v[72:73], v[78:79], v[0:1], v[108:109] op_sel_hi:[1,0,1] neg_lo:[0,0,1] neg_hi:[0,0,1]
	v_pk_fma_f32 v[78:79], v[76:77], v[76:77], v[96:97]
	v_mul_f32_e32 v96, v77, v77
	v_pk_add_f32 v[78:79], v[78:79], v[96:97] op_sel_hi:[1,0]
	v_mul_f32_e32 v96, v73, v73
	v_pk_fma_f32 v[78:79], v[72:73], v[72:73], v[78:79]
	v_mul_f32_e32 v94, v41, v41
	v_pk_add_f32 v[96:97], v[78:79], v[96:97] op_sel_hi:[1,0]
	v_pk_fma_f32 v[78:79], v[48:49], v[0:1], v[110:111] op_sel_hi:[1,0,1] neg_lo:[0,0,1] neg_hi:[0,0,1]
	s_waitcnt lgkmcnt(9)
	v_pk_fma_f32 v[44:45], v[44:45], v[0:1], v[90:91] op_sel_hi:[1,0,1] neg_lo:[0,0,1] neg_hi:[0,0,1]
	v_pk_fma_f32 v[48:49], v[78:79], v[78:79], v[96:97]
	v_mul_f32_e32 v96, v79, v79
	v_pk_add_f32 v[48:49], v[48:49], v[96:97] op_sel_hi:[1,0]
	v_mul_f32_e32 v96, v51, v51
	v_pk_fma_f32 v[48:49], v[50:51], v[50:51], v[48:49]
	v_mul_f32_e32 v90, v45, v45
	v_pk_add_f32 v[96:97], v[48:49], v[96:97] op_sel_hi:[1,0]
	v_pk_fma_f32 v[48:49], v[54:55], v[0:1], v[116:117] op_sel_hi:[1,0,1] neg_lo:[0,0,1] neg_hi:[0,0,1]
	v_pk_fma_f32 v[54:55], v[52:53], v[0:1], v[114:115] op_sel_hi:[1,0,1] neg_lo:[0,0,1] neg_hi:[0,0,1]
	s_waitcnt lgkmcnt(8)
	v_pk_fma_f32 v[46:47], v[46:47], v[0:1], v[92:93] op_sel_hi:[1,0,1] neg_lo:[0,0,1] neg_hi:[0,0,1]
	v_pk_fma_f32 v[52:53], v[54:55], v[54:55], v[96:97]
	v_mul_f32_e32 v96, v55, v55
	v_pk_add_f32 v[52:53], v[52:53], v[96:97] op_sel_hi:[1,0]
	v_mul_f32_e32 v96, v49, v49
	v_pk_fma_f32 v[52:53], v[48:49], v[48:49], v[52:53]
	s_waitcnt lgkmcnt(7)
	v_pk_fma_f32 v[16:17], v[16:17], v[0:1], v[86:87] op_sel_hi:[1,0,1] neg_lo:[0,0,1] neg_hi:[0,0,1]
	v_pk_add_f32 v[96:97], v[52:53], v[96:97] op_sel_hi:[1,0]
	v_pk_fma_f32 v[52:53], v[58:59], v[0:1], v[120:121] op_sel_hi:[1,0,1] neg_lo:[0,0,1] neg_hi:[0,0,1]
	v_pk_fma_f32 v[58:59], v[56:57], v[0:1], v[118:119] op_sel_hi:[1,0,1] neg_lo:[0,0,1] neg_hi:[0,0,1]
	v_mul_f32_e32 v86, v17, v17
	v_pk_fma_f32 v[56:57], v[58:59], v[58:59], v[96:97]
	v_mul_f32_e32 v96, v59, v59
	v_pk_add_f32 v[56:57], v[56:57], v[96:97] op_sel_hi:[1,0]
	v_mul_f32_e32 v96, v53, v53
	v_pk_fma_f32 v[56:57], v[52:53], v[52:53], v[56:57]
	s_waitcnt lgkmcnt(6)
	v_pk_fma_f32 v[18:19], v[18:19], v[0:1], v[88:89] op_sel_hi:[1,0,1] neg_lo:[0,0,1] neg_hi:[0,0,1]
	v_pk_add_f32 v[96:97], v[56:57], v[96:97] op_sel_hi:[1,0]
	v_pk_fma_f32 v[56:57], v[62:63], v[0:1], v[124:125] op_sel_hi:[1,0,1] neg_lo:[0,0,1] neg_hi:[0,0,1]
	v_pk_fma_f32 v[62:63], v[60:61], v[60:61], v[96:97]
	v_mul_f32_e32 v96, v61, v61
	v_pk_add_f32 v[62:63], v[62:63], v[96:97] op_sel_hi:[1,0]
	v_mul_f32_e32 v96, v57, v57
	v_pk_fma_f32 v[62:63], v[56:57], v[56:57], v[62:63]
	s_waitcnt lgkmcnt(5)
	v_pk_fma_f32 v[20:21], v[20:21], v[0:1], v[82:83] op_sel_hi:[1,0,1] neg_lo:[0,0,1] neg_hi:[0,0,1]
	v_pk_add_f32 v[96:97], v[62:63], v[96:97] op_sel_hi:[1,0]
	v_pk_fma_f32 v[62:63], v[32:33], v[0:1], v[126:127] op_sel_hi:[1,0,1] neg_lo:[0,0,1] neg_hi:[0,0,1]
	v_mul_f32_e32 v82, v21, v21
	v_pk_fma_f32 v[32:33], v[62:63], v[62:63], v[96:97]
	v_mul_f32_e32 v96, v63, v63
	v_pk_add_f32 v[32:33], v[32:33], v[96:97] op_sel_hi:[1,0]
	v_mul_f32_e32 v96, v35, v35
	v_pk_fma_f32 v[32:33], v[34:35], v[34:35], v[32:33]
	s_waitcnt lgkmcnt(4)
	v_pk_fma_f32 v[22:23], v[22:23], v[0:1], v[84:85] op_sel_hi:[1,0,1] neg_lo:[0,0,1] neg_hi:[0,0,1]
	v_pk_add_f32 v[96:97], v[32:33], v[96:97] op_sel_hi:[1,0]
	v_pk_fma_f32 v[32:33], v[38:39], v[0:1], v[132:133] op_sel_hi:[1,0,1] neg_lo:[0,0,1] neg_hi:[0,0,1]
	v_pk_fma_f32 v[38:39], v[36:37], v[0:1], v[130:131] op_sel_hi:[1,0,1] neg_lo:[0,0,1] neg_hi:[0,0,1]
	s_waitcnt lgkmcnt(3)
	v_pk_fma_f32 v[14:15], v[24:25], v[0:1], v[14:15] op_sel_hi:[1,0,1] neg_lo:[0,0,1] neg_hi:[0,0,1]
	v_pk_fma_f32 v[36:37], v[38:39], v[38:39], v[96:97]
	v_mul_f32_e32 v96, v39, v39
	v_pk_add_f32 v[36:37], v[36:37], v[96:97] op_sel_hi:[1,0]
	v_mul_f32_e32 v96, v33, v33
	v_pk_fma_f32 v[36:37], v[32:33], v[32:33], v[36:37]
	s_waitcnt lgkmcnt(2)
	v_pk_fma_f32 v[26:27], v[26:27], v[0:1], v[80:81] op_sel_hi:[1,0,1] neg_lo:[0,0,1] neg_hi:[0,0,1]
	v_pk_add_f32 v[96:97], v[36:37], v[96:97] op_sel_hi:[1,0]
	v_pk_fma_f32 v[36:37], v[42:43], v[0:1], v[134:135] op_sel_hi:[1,0,1] neg_lo:[0,0,1] neg_hi:[0,0,1]
	v_pk_fma_f32 v[42:43], v[40:41], v[40:41], v[96:97]
	s_waitcnt lgkmcnt(1)
	v_pk_fma_f32 v[10:11], v[28:29], v[0:1], v[10:11] op_sel_hi:[1,0,1] neg_lo:[0,0,1] neg_hi:[0,0,1]
	v_pk_add_f32 v[42:43], v[42:43], v[94:95] op_sel_hi:[1,0]
	v_mul_f32_e32 v94, v37, v37
	v_pk_fma_f32 v[42:43], v[36:37], v[36:37], v[42:43]
	s_waitcnt lgkmcnt(0)
	v_pk_fma_f32 v[12:13], v[30:31], v[0:1], v[12:13] op_sel_hi:[1,0,1] neg_lo:[0,0,1] neg_hi:[0,0,1]
	v_pk_add_f32 v[42:43], v[42:43], v[94:95] op_sel_hi:[1,0]
	v_mul_f32_e32 v0, v11, v11
	v_pk_fma_f32 v[42:43], v[44:45], v[44:45], v[42:43]
	v_readlane_b32 s52, v239, 32
	v_pk_add_f32 v[42:43], v[42:43], v[90:91] op_sel_hi:[1,0]
	v_mul_f32_e32 v90, v47, v47
	v_pk_fma_f32 v[42:43], v[46:47], v[46:47], v[42:43]
	v_readlane_b32 s53, v239, 33
	v_pk_add_f32 v[42:43], v[42:43], v[90:91] op_sel_hi:[1,0]
	s_lshl_b32 s0, s49, 1
	v_pk_fma_f32 v[42:43], v[16:17], v[16:17], v[42:43]
	v_lshl_add_u64 v[6:7], v[158:159], 1, s[52:53]
	v_pk_add_f32 v[42:43], v[42:43], v[86:87] op_sel_hi:[1,0]
	v_mul_f32_e32 v86, v19, v19
	v_pk_fma_f32 v[42:43], v[18:19], v[18:19], v[42:43]
	v_lshl_add_u64 v[6:7], v[6:7], 0, s[0:1]
	v_pk_add_f32 v[42:43], v[42:43], v[86:87] op_sel_hi:[1,0]
	v_readlane_b32 s54, v239, 34
	v_pk_fma_f32 v[42:43], v[20:21], v[20:21], v[42:43]
	v_readlane_b32 s55, v239, 35
	v_pk_add_f32 v[42:43], v[42:43], v[82:83] op_sel_hi:[1,0]
	v_mul_f32_e32 v82, v23, v23
	v_pk_fma_f32 v[42:43], v[22:23], v[22:23], v[42:43]
	v_readlane_b32 s56, v239, 36
	v_pk_add_f32 v[42:43], v[42:43], v[82:83] op_sel_hi:[1,0]
	v_readlane_b32 s57, v239, 37
	v_pk_fma_f32 v[24:25], v[14:15], v[14:15], v[42:43]
	v_mul_f32_e32 v42, v15, v15
	v_pk_add_f32 v[24:25], v[24:25], v[42:43] op_sel_hi:[1,0]
	v_mul_f32_e32 v42, v27, v27
	v_pk_fma_f32 v[24:25], v[26:27], v[26:27], v[24:25]
	v_readlane_b32 s58, v239, 38
	v_pk_add_f32 v[24:25], v[24:25], v[42:43] op_sel_hi:[1,0]
	v_readlane_b32 s59, v239, 39
	v_pk_fma_f32 v[24:25], v[10:11], v[10:11], v[24:25]
	v_readlane_b32 s65, v239, 1
	v_pk_add_f32 v[24:25], v[24:25], v[0:1] op_sel_hi:[1,0]
	v_mul_f32_e32 v0, v13, v13
	v_pk_fma_f32 v[24:25], v[12:13], v[12:13], v[24:25]
	v_readlane_b32 s66, v239, 2
	v_pk_add_f32 v[24:25], v[24:25], v[0:1] op_sel_hi:[1,0]
	v_readlane_b32 s67, v239, 3
	v_mov_b32_e32 v0, v24
	s_nop 1
	v_permlane32_swap_b32_e32 v24, v0
	v_add_f32_e32 v0, v24, v0
	v_fmamk_f32 v0, v0, 0x3c000000, v157
	v_mul_f32_e32 v24, 0x4b800000, v0
	v_cmp_gt_f32_e32 vcc, s46, v0
	v_readlane_b32 s68, v239, 4
	v_readlane_b32 s69, v239, 5
	v_cndmask_b32_e32 v0, v0, v24, vcc
	v_rsq_f32_e32 v24, v0
	v_lshlrev_b32_e32 v0, 3, v168
	v_lshl_add_u64 v[6:7], v[6:7], 0, v[0:1]
	v_readlane_b32 s70, v239, 6
	v_mul_f32_e32 v0, 0x45800000, v24
	v_cndmask_b32_e32 v0, v24, v0, vcc
	v_mul_f32_e32 v0, 0x3f4ccccd, v0
	v_pk_mul_f32 v[24:25], v[66:67], v[0:1] op_sel_hi:[1,0]
	v_pk_mul_f32 v[8:9], v[8:9], v[0:1] op_sel_hi:[1,0]
	s_waitcnt vmcnt(0)
	v_pk_mul_f32 v[2:3], v[2:3], v[24:25]
	v_pk_mul_f32 v[4:5], v[4:5], v[8:9]
	v_cvt_pk_bf16_f32 v2, v2, v3
	v_cvt_pk_bf16_f32 v3, v4, v5
	global_store_dwordx2 v[6:7], v[2:3], off
	global_load_dwordx4 v[80:83], v146, s[74:75] offset:32
	global_load_dwordx4 v[84:87], v146, s[74:75] offset:64
	global_load_dwordx4 v[88:91], v146, s[74:75] offset:96
	global_load_dwordx4 v[92:95], v146, s[74:75] offset:128
	global_load_dwordx4 v[96:99], v146, s[74:75] offset:160
	global_load_dwordx4 v[100:103], v146, s[74:75] offset:192
	global_load_dwordx4 v[104:107], v146, s[74:75] offset:224
	global_load_dwordx4 v[108:111], v146, s[74:75] offset:256
	global_load_dwordx4 v[112:115], v146, s[74:75] offset:288
	global_load_dwordx4 v[116:119], v146, s[74:75] offset:320
	global_load_dwordx4 v[120:123], v146, s[74:75] offset:352
	global_load_dwordx4 v[124:127], v146, s[74:75] offset:384
	global_load_dwordx4 v[128:131], v146, s[74:75] offset:416
	global_load_dwordx4 v[132:135], v146, s[74:75] offset:448
	global_load_dwordx4 v[240:243], v146, s[74:75] offset:480
	v_pk_mul_f32 v[8:9], v[70:71], v[0:1] op_sel_hi:[1,0]
	v_pk_mul_f32 v[24:25], v[68:69], v[0:1] op_sel_hi:[1,0]
	v_readlane_b32 s71, v239, 7
	v_readlane_b32 s72, v239, 8
	v_readlane_b32 s73, v239, 9
	v_readlane_b32 s76, v239, 12
	v_readlane_b32 s77, v239, 13
	v_readlane_b32 s78, v239, 14
	v_readlane_b32 s79, v239, 15
	s_waitcnt vmcnt(14)
	v_pk_mul_f32 v[80:81], v[80:81], v[8:9]
	v_pk_mul_f32 v[8:9], v[64:65], v[0:1] op_sel_hi:[1,0]
	v_cvt_pk_bf16_f32 v80, v80, v81
	v_pk_mul_f32 v[82:83], v[82:83], v[8:9]
	v_pk_mul_f32 v[8:9], v[74:75], v[0:1] op_sel_hi:[1,0]
	v_cvt_pk_bf16_f32 v81, v82, v83
	global_store_dwordx2 v[6:7], v[80:81], off offset:16
	s_waitcnt vmcnt(14)
	v_pk_mul_f32 v[84:85], v[8:9], v[84:85]
	v_pk_mul_f32 v[86:87], v[24:25], v[86:87]
	v_cvt_pk_bf16_f32 v84, v84, v85
	v_cvt_pk_bf16_f32 v85, v86, v87
	global_store_dwordx2 v[6:7], v[84:85], off offset:32
	v_pk_mul_f32 v[8:9], v[76:77], v[0:1] op_sel_hi:[1,0]
	v_pk_mul_f32 v[24:25], v[72:73], v[0:1] op_sel_hi:[1,0]
	s_waitcnt vmcnt(14)
	v_pk_mul_f32 v[88:89], v[8:9], v[88:89]
	v_pk_mul_f32 v[90:91], v[24:25], v[90:91]
	v_cvt_pk_bf16_f32 v88, v88, v89
	v_cvt_pk_bf16_f32 v89, v90, v91
	global_store_dwordx2 v[6:7], v[88:89], off offset:48
	v_pk_mul_f32 v[8:9], v[78:79], v[0:1] op_sel_hi:[1,0]
	v_pk_mul_f32 v[24:25], v[50:51], v[0:1] op_sel_hi:[1,0]
	s_waitcnt vmcnt(14)
	v_pk_mul_f32 v[92:93], v[8:9], v[92:93]
	v_pk_mul_f32 v[94:95], v[24:25], v[94:95]
	v_cvt_pk_bf16_f32 v92, v92, v93
	v_cvt_pk_bf16_f32 v93, v94, v95
	global_store_dwordx2 v[6:7], v[92:93], off offset:64
	v_pk_mul_f32 v[8:9], v[54:55], v[0:1] op_sel_hi:[1,0]
	v_pk_mul_f32 v[24:25], v[48:49], v[0:1] op_sel_hi:[1,0]
	s_waitcnt vmcnt(14)
	v_pk_mul_f32 v[96:97], v[8:9], v[96:97]
	v_pk_mul_f32 v[98:99], v[24:25], v[98:99]
	v_cvt_pk_bf16_f32 v96, v96, v97
	v_cvt_pk_bf16_f32 v97, v98, v99
	global_store_dwordx2 v[6:7], v[96:97], off offset:80
	v_pk_mul_f32 v[8:9], v[58:59], v[0:1] op_sel_hi:[1,0]
	v_pk_mul_f32 v[24:25], v[52:53], v[0:1] op_sel_hi:[1,0]
	s_waitcnt vmcnt(14)
	v_pk_mul_f32 v[100:101], v[8:9], v[100:101]
	v_pk_mul_f32 v[102:103], v[24:25], v[102:103]
	v_cvt_pk_bf16_f32 v100, v100, v101
	v_cvt_pk_bf16_f32 v101, v102, v103
	global_store_dwordx2 v[6:7], v[100:101], off offset:96
	v_pk_mul_f32 v[8:9], v[60:61], v[0:1] op_sel_hi:[1,0]
	v_pk_mul_f32 v[24:25], v[56:57], v[0:1] op_sel_hi:[1,0]
	s_waitcnt vmcnt(14)
	v_pk_mul_f32 v[104:105], v[8:9], v[104:105]
	v_pk_mul_f32 v[106:107], v[24:25], v[106:107]
	v_cvt_pk_bf16_f32 v104, v104, v105
	v_cvt_pk_bf16_f32 v105, v106, v107
	global_store_dwordx2 v[6:7], v[104:105], off offset:112
	v_pk_mul_f32 v[8:9], v[62:63], v[0:1] op_sel_hi:[1,0]
	v_pk_mul_f32 v[24:25], v[34:35], v[0:1] op_sel_hi:[1,0]
	s_waitcnt vmcnt(14)
	v_pk_mul_f32 v[108:109], v[8:9], v[108:109]
	v_pk_mul_f32 v[110:111], v[24:25], v[110:111]
	v_cvt_pk_bf16_f32 v108, v108, v109
	v_cvt_pk_bf16_f32 v109, v110, v111
	global_store_dwordx2 v[6:7], v[108:109], off offset:128
	v_pk_mul_f32 v[8:9], v[38:39], v[0:1] op_sel_hi:[1,0]
	v_pk_mul_f32 v[24:25], v[32:33], v[0:1] op_sel_hi:[1,0]
	s_waitcnt vmcnt(14)
	v_pk_mul_f32 v[112:113], v[8:9], v[112:113]
	v_pk_mul_f32 v[114:115], v[24:25], v[114:115]
	v_cvt_pk_bf16_f32 v112, v112, v113
	v_cvt_pk_bf16_f32 v113, v114, v115
	global_store_dwordx2 v[6:7], v[112:113], off offset:144
	v_pk_mul_f32 v[8:9], v[40:41], v[0:1] op_sel_hi:[1,0]
	v_pk_mul_f32 v[24:25], v[36:37], v[0:1] op_sel_hi:[1,0]
	s_waitcnt vmcnt(14)
	v_pk_mul_f32 v[116:117], v[8:9], v[116:117]
	v_pk_mul_f32 v[118:119], v[24:25], v[118:119]
	v_cvt_pk_bf16_f32 v116, v116, v117
	v_cvt_pk_bf16_f32 v117, v118, v119
	global_store_dwordx2 v[6:7], v[116:117], off offset:160
	v_pk_mul_f32 v[8:9], v[44:45], v[0:1] op_sel_hi:[1,0]
	v_pk_mul_f32 v[24:25], v[46:47], v[0:1] op_sel_hi:[1,0]
	s_waitcnt vmcnt(14)
	v_pk_mul_f32 v[120:121], v[8:9], v[120:121]
	v_pk_mul_f32 v[122:123], v[24:25], v[122:123]
	v_cvt_pk_bf16_f32 v120, v120, v121
	v_cvt_pk_bf16_f32 v121, v122, v123
	global_store_dwordx2 v[6:7], v[120:121], off offset:176
	v_pk_mul_f32 v[8:9], v[16:17], v[0:1] op_sel_hi:[1,0]
	v_pk_mul_f32 v[16:17], v[18:19], v[0:1] op_sel_hi:[1,0]
	s_waitcnt vmcnt(14)
	v_pk_mul_f32 v[124:125], v[8:9], v[124:125]
	v_pk_mul_f32 v[126:127], v[16:17], v[126:127]
	v_cvt_pk_bf16_f32 v124, v124, v125
	v_cvt_pk_bf16_f32 v125, v126, v127
	global_store_dwordx2 v[6:7], v[124:125], off offset:192
	v_pk_mul_f32 v[8:9], v[20:21], v[0:1] op_sel_hi:[1,0]
	v_pk_mul_f32 v[16:17], v[22:23], v[0:1] op_sel_hi:[1,0]
	s_waitcnt vmcnt(14)
	v_pk_mul_f32 v[128:129], v[8:9], v[128:129]
	v_pk_mul_f32 v[130:131], v[16:17], v[130:131]
	v_cvt_pk_bf16_f32 v128, v128, v129
	v_cvt_pk_bf16_f32 v129, v130, v131
	global_store_dwordx2 v[6:7], v[128:129], off offset:208
	v_pk_mul_f32 v[8:9], v[14:15], v[0:1] op_sel_hi:[1,0]
	v_pk_mul_f32 v[14:15], v[26:27], v[0:1] op_sel_hi:[1,0]
	s_waitcnt vmcnt(14)
	v_pk_mul_f32 v[132:133], v[8:9], v[132:133]
	v_pk_mul_f32 v[134:135], v[14:15], v[134:135]
	v_cvt_pk_bf16_f32 v132, v132, v133
	v_cvt_pk_bf16_f32 v133, v134, v135
	global_store_dwordx2 v[6:7], v[132:133], off offset:224
	v_pk_mul_f32 v[8:9], v[10:11], v[0:1] op_sel_hi:[1,0]
	v_pk_mul_f32 v[10:11], v[12:13], v[0:1] op_sel_hi:[1,0]
	s_waitcnt vmcnt(14)
	v_pk_mul_f32 v[240:241], v[8:9], v[240:241]
	v_pk_mul_f32 v[242:243], v[10:11], v[242:243]
	v_cvt_pk_bf16_f32 v240, v240, v241
	v_cvt_pk_bf16_f32 v241, v242, v243
	global_store_dwordx2 v[6:7], v[240:241], off offset:240
	s_branch .LBB0_279
